# v18_mobacopy2
# speedup vs baseline: 1.0051x; 1.0051x over previous
; DEVI float bfs(short h) { return __uint_as_float(((unsigned)(u16)h) << 16); }
; DEVI float silu_f(float x) { return x * __builtin_amdgcn_rcpf(1.f + __expf(-x)); }
; DEVI float xq_sum(float v) { v += __shfl_xor(v, 16); v += __shfl_xor(v, 32); return v; }
; DEVI void moba_item(const Params& p, int l, int item) {
;     ...
;   lsum = xq_sum(lsum);
;   const float inv = __builtin_amdgcn_rcpf(lsum);
;   const long qtok = t0 + w * 16 + fr;
;   bf16x4 gtv[8];
; #pragma unroll
;   for (int ct = 0; ct < 8; ++ct) gtv[ct] = *(const bf16x4*)(proj + qtok * NP + C_CGATE + h * 128 + ct * 16 + fq * 4);
; #pragma unroll
;   for (int ct = 0; ct < 8; ++ct) {
;     int dv = ct * 16 + fq * 4;
;     const bf16x4 gt = gtv[ct];
;     *(bf16x4*)(p.ys + (long)2 * T_ * 1024 + qtok * 1024 + h * 128 + dv) =
;         pack4(oacc[ct][0] * inv * silu_f(bfs(gt[0])), oacc[ct][1] * inv * silu_f(bfs(gt[1])),
;               oacc[ct][2] * inv * silu_f(bfs(gt[2])), oacc[ct][3] * inv * silu_f(bfs(gt[3])));
;   }
.LBB0_493:
	v_cmp_lt_i32_e32 vcc, v232, v252
	v_or_b32_e32 v210, s27, v156
	s_waitcnt vmcnt(5)
	v_lshlrev_b32_e32 v10, 1, v158
	v_cndmask_b32_e32 v0, v235, v232, vcc
	v_lshlrev_b32_e32 v0, 2, v0
	ds_bpermute_b32 v0, v0, v166
	v_cmp_lt_i32_e32 vcc, v226, v252
	v_mov_b32_e32 v11, v211
	s_waitcnt lgkmcnt(0)
	v_add_f32_e32 v0, v166, v0
	v_cndmask_b32_e32 v1, v235, v226, vcc
	v_lshlrev_b32_e32 v1, 2, v1
	ds_bpermute_b32 v1, v1, v0
	s_waitcnt vmcnt(2) lgkmcnt(0)
	v_add_f32_e32 v20, v0, v1
	v_mov_b64_e32 v[0:1], s[92:93]
	v_mad_u64_u32 v[0:1], s[2:3], v210, s97, v[0:1]
	v_lshl_add_u64 v[0:1], v[0:1], 0, s[98:99]
	v_lshl_add_u64 v[0:1], v[0:1], 0, v[10:11]
	s_mov_b64 s[2:3], 0x4200
	v_lshl_add_u64 v[2:3], v[0:1], 0, s[2:3]
	s_movk_i32 s2, 0x4000
	v_add_co_u32_e32 v0, vcc, s2, v0
	s_brev_b32 s2, 64
	s_nop 0
	v_addc_co_u32_e32 v1, vcc, 0, v1, vcc
	s_nop 0
	v_rcp_f32_e32 v0, v20
	v_lshlrev_b64 v[20:21], 11, v[210:211]
	s_waitcnt vmcnt(0)
	v_lshlrev_b32_e32 v22, 16, v180
	v_mul_f32_e32 v1, 0xbfb8aa3b, v22
	v_exp_f32_e32 v1, v1
	v_and_b32_e32 v23, 0xffff0000, v180
	v_add_f32_e32 v1, 1.0, v1
	v_rcp_f32_e32 v24, v1
	v_pk_mul_f32 v[26:27], v[48:49], v[0:1] op_sel_hi:[1, 0]
	v_mul_f32_e32 v1, 0xbfb8aa3b, v23
	v_exp_f32_e32 v1, v1
	s_nop 0
	v_add_f32_e32 v1, 1.0, v1
	v_rcp_f32_e32 v25, v1
	s_nop 0
	v_pk_mul_f32 v[22:23], v[24:25], v[22:23]
	v_lshlrev_b32_e32 v24, 16, v181
	v_mul_f32_e32 v1, 0xbfb8aa3b, v24
	v_exp_f32_e32 v1, v1
	v_and_b32_e32 v25, 0xffff0000, v181
	v_pk_mul_f32 v[22:23], v[26:27], v[22:23]
	v_add_f32_e32 v1, 1.0, v1
	v_rcp_f32_e32 v16, v1
	v_pk_mul_f32 v[26:27], v[50:51], v[0:1] op_sel_hi:[1, 0]
	v_mul_f32_e32 v1, 0xbfb8aa3b, v25
	v_exp_f32_e32 v1, v1
	v_cvt_pk_bf16_f32 v22, v22, v23
	v_add_f32_e32 v1, 1.0, v1
	v_rcp_f32_e32 v17, v1
	s_nop 0
	v_pk_mul_f32 v[16:17], v[16:17], v[24:25]
	s_nop 0
	v_pk_mul_f32 v[16:17], v[26:27], v[16:17]
	s_nop 0
	v_cvt_pk_bf16_f32 v23, v16, v17
	v_lshl_add_u64 v[16:17], s[18:19], 0, v[20:21]
	v_lshl_add_u64 v[16:17], v[16:17], 0, s[98:99]
	v_lshl_add_u64 v[16:17], v[16:17], 0, v[10:11]
	global_store_dwordx2 v[16:17], v[22:23], off
	s_waitcnt vmcnt(7)
	v_lshlrev_b32_e32 v16, 16, v182
	v_mul_f32_e32 v1, 0xbfb8aa3b, v16
	v_exp_f32_e32 v1, v1
	v_and_b32_e32 v17, 0xffff0000, v182
	v_add_f32_e32 v1, 1.0, v1
	v_rcp_f32_e32 v22, v1
	v_pk_mul_f32 v[24:25], v[52:53], v[0:1] op_sel_hi:[1, 0]
	v_mul_f32_e32 v1, 0xbfb8aa3b, v17
	v_exp_f32_e32 v1, v1
	s_nop 0
	v_add_f32_e32 v1, 1.0, v1
	v_rcp_f32_e32 v23, v1
	s_nop 0
	v_pk_mul_f32 v[16:17], v[22:23], v[16:17]
	v_lshlrev_b32_e32 v22, 16, v183
	v_mul_f32_e32 v1, 0xbfb8aa3b, v22
	v_exp_f32_e32 v1, v1
	v_and_b32_e32 v23, 0xffff0000, v183
	v_pk_mul_f32 v[16:17], v[24:25], v[16:17]
	v_add_f32_e32 v1, 1.0, v1
	v_rcp_f32_e32 v18, v1
	v_pk_mul_f32 v[24:25], v[54:55], v[0:1] op_sel_hi:[1, 0]
	v_mul_f32_e32 v1, 0xbfb8aa3b, v23
	v_exp_f32_e32 v1, v1
	v_cvt_pk_bf16_f32 v16, v16, v17
	v_add_f32_e32 v1, 1.0, v1
	v_rcp_f32_e32 v19, v1
	s_nop 0
	v_pk_mul_f32 v[18:19], v[18:19], v[22:23]
	s_nop 0
	v_pk_mul_f32 v[18:19], v[24:25], v[18:19]
	s_nop 0
	v_cvt_pk_bf16_f32 v17, v18, v19
	v_lshl_add_u64 v[18:19], s[14:15], 0, v[20:21]
	v_lshl_add_u64 v[18:19], v[18:19], 0, s[98:99]
	v_lshl_add_u64 v[10:11], v[18:19], 0, v[10:11]
	v_add_co_u32_e32 v10, vcc, s2, v10
	s_nop 1
	v_addc_co_u32_e32 v11, vcc, 0, v11, vcc
	global_store_dwordx2 v[10:11], v[16:17], off offset:32
	s_waitcnt vmcnt(7)
	v_lshlrev_b32_e32 v16, 16, v184
	v_mul_f32_e32 v1, 0xbfb8aa3b, v16
	v_exp_f32_e32 v1, v1
	v_and_b32_e32 v17, 0xffff0000, v184
	v_add_f32_e32 v1, 1.0, v1
	v_rcp_f32_e32 v18, v1
	v_pk_mul_f32 v[20:21], v[56:57], v[0:1] op_sel_hi:[1, 0]
	v_mul_f32_e32 v1, 0xbfb8aa3b, v17
	v_exp_f32_e32 v1, v1
	s_nop 0
	v_add_f32_e32 v1, 1.0, v1
	v_rcp_f32_e32 v19, v1
	s_nop 0
	v_pk_mul_f32 v[16:17], v[18:19], v[16:17]
	v_lshlrev_b32_e32 v18, 16, v185
	v_mul_f32_e32 v1, 0xbfb8aa3b, v18
	v_exp_f32_e32 v1, v1
	v_and_b32_e32 v19, 0xffff0000, v185
	v_pk_mul_f32 v[16:17], v[20:21], v[16:17]
	v_add_f32_e32 v1, 1.0, v1
	v_rcp_f32_e32 v14, v1
	v_pk_mul_f32 v[20:21], v[58:59], v[0:1] op_sel_hi:[1, 0]
	v_mul_f32_e32 v1, 0xbfb8aa3b, v19
	v_exp_f32_e32 v1, v1
	v_cvt_pk_bf16_f32 v16, v16, v17
	v_add_f32_e32 v1, 1.0, v1
	v_rcp_f32_e32 v15, v1
	s_nop 0
	v_pk_mul_f32 v[14:15], v[14:15], v[18:19]
	s_nop 0
	v_pk_mul_f32 v[14:15], v[20:21], v[14:15]
	s_nop 0
	v_cvt_pk_bf16_f32 v17, v14, v15
	s_waitcnt vmcnt(6)
; DEVI float bfs(short h) { return __uint_as_float(((unsigned)(u16)h) << 16); }
; DEVI float silu_f(float x) { return x * __builtin_amdgcn_rcpf(1.f + __expf(-x)); }
; DEVI void moba_item(const Params& p, int l, int item) {
;     ...
; #pragma unroll
;   for (int ct = 0; ct < 8; ++ct) {
;     int dv = ct * 16 + fq * 4;
;     const bf16x4 gt = gtv[ct];
;     *(bf16x4*)(p.ys + (long)2 * T_ * 1024 + qtok * 1024 + h * 128 + dv) =
;         pack4(oacc[ct][0] * inv * silu_f(bfs(gt[0])), oacc[ct][1] * inv * silu_f(bfs(gt[1])),
;               oacc[ct][2] * inv * silu_f(bfs(gt[2])), oacc[ct][3] * inv * silu_f(bfs(gt[3])));
;   }
	v_lshlrev_b32_e32 v14, 16, v186
	v_mul_f32_e32 v1, 0xbfb8aa3b, v14
	v_exp_f32_e32 v1, v1
	v_and_b32_e32 v15, 0xffff0000, v186
	global_store_dwordx2 v[10:11], v[16:17], off offset:64
	v_add_f32_e32 v1, 1.0, v1
	v_rcp_f32_e32 v16, v1
	v_pk_mul_f32 v[18:19], v[60:61], v[0:1] op_sel_hi:[1, 0]
	v_mul_f32_e32 v1, 0xbfb8aa3b, v15
	v_exp_f32_e32 v1, v1
	s_nop 0
	v_add_f32_e32 v1, 1.0, v1
	v_rcp_f32_e32 v17, v1
	s_nop 0
	v_pk_mul_f32 v[14:15], v[16:17], v[14:15]
	v_lshlrev_b32_e32 v16, 16, v187
	v_mul_f32_e32 v1, 0xbfb8aa3b, v16
	v_exp_f32_e32 v1, v1
	v_and_b32_e32 v17, 0xffff0000, v187
	v_pk_mul_f32 v[14:15], v[18:19], v[14:15]
	v_add_f32_e32 v1, 1.0, v1
	v_rcp_f32_e32 v12, v1
	v_pk_mul_f32 v[18:19], v[62:63], v[0:1] op_sel_hi:[1, 0]
	v_mul_f32_e32 v1, 0xbfb8aa3b, v17
	v_exp_f32_e32 v1, v1
	v_cvt_pk_bf16_f32 v14, v14, v15
	v_add_f32_e32 v1, 1.0, v1
	v_rcp_f32_e32 v13, v1
	s_nop 0
	v_pk_mul_f32 v[12:13], v[12:13], v[16:17]
	s_nop 0
	v_pk_mul_f32 v[12:13], v[18:19], v[12:13]
	s_nop 0
	v_cvt_pk_bf16_f32 v15, v12, v13
	s_waitcnt vmcnt(6)
	v_lshlrev_b32_e32 v12, 16, v188
	v_mul_f32_e32 v1, 0xbfb8aa3b, v12
	v_exp_f32_e32 v1, v1
	v_and_b32_e32 v13, 0xffff0000, v188
	global_store_dwordx2 v[10:11], v[14:15], off offset:96
	v_add_f32_e32 v1, 1.0, v1
	v_rcp_f32_e32 v14, v1
	v_pk_mul_f32 v[16:17], v[64:65], v[0:1] op_sel_hi:[1, 0]
	v_mul_f32_e32 v1, 0xbfb8aa3b, v13
	v_exp_f32_e32 v1, v1
	s_nop 0
	v_add_f32_e32 v1, 1.0, v1
	v_rcp_f32_e32 v15, v1
	s_nop 0
	v_pk_mul_f32 v[12:13], v[14:15], v[12:13]
	v_lshlrev_b32_e32 v14, 16, v189
	v_mul_f32_e32 v1, 0xbfb8aa3b, v14
	v_exp_f32_e32 v1, v1
	v_and_b32_e32 v15, 0xffff0000, v189
	v_pk_mul_f32 v[12:13], v[16:17], v[12:13]
	v_add_f32_e32 v1, 1.0, v1
	v_rcp_f32_e32 v8, v1
	v_pk_mul_f32 v[16:17], v[66:67], v[0:1] op_sel_hi:[1, 0]
	v_mul_f32_e32 v1, 0xbfb8aa3b, v15
	v_exp_f32_e32 v1, v1
	v_cvt_pk_bf16_f32 v12, v12, v13
	v_add_f32_e32 v1, 1.0, v1
	v_rcp_f32_e32 v9, v1
	s_nop 0
	v_pk_mul_f32 v[8:9], v[8:9], v[14:15]
	s_nop 0
	v_pk_mul_f32 v[8:9], v[16:17], v[8:9]
	s_nop 0
	v_cvt_pk_bf16_f32 v13, v8, v9
	s_waitcnt vmcnt(6)
	v_lshlrev_b32_e32 v8, 16, v190
	v_mul_f32_e32 v1, 0xbfb8aa3b, v8
	v_exp_f32_e32 v1, v1
	v_and_b32_e32 v9, 0xffff0000, v190
	global_store_dwordx2 v[10:11], v[12:13], off offset:128
	v_add_f32_e32 v1, 1.0, v1
	v_rcp_f32_e32 v12, v1
	v_pk_mul_f32 v[14:15], v[68:69], v[0:1] op_sel_hi:[1, 0]
	v_mul_f32_e32 v1, 0xbfb8aa3b, v9
	v_exp_f32_e32 v1, v1
	s_nop 0
	v_add_f32_e32 v1, 1.0, v1
	v_rcp_f32_e32 v13, v1
	s_nop 0
	v_pk_mul_f32 v[8:9], v[12:13], v[8:9]
	v_lshlrev_b32_e32 v12, 16, v191
	v_mul_f32_e32 v1, 0xbfb8aa3b, v12
	v_exp_f32_e32 v1, v1
	v_and_b32_e32 v13, 0xffff0000, v191
	v_pk_mul_f32 v[8:9], v[14:15], v[8:9]
	v_add_f32_e32 v1, 1.0, v1
	v_rcp_f32_e32 v6, v1
	v_pk_mul_f32 v[14:15], v[70:71], v[0:1] op_sel_hi:[1, 0]
	v_mul_f32_e32 v1, 0xbfb8aa3b, v13
	v_exp_f32_e32 v1, v1
	v_cvt_pk_bf16_f32 v8, v8, v9
	v_add_f32_e32 v1, 1.0, v1
	v_rcp_f32_e32 v7, v1
	s_nop 0
	v_pk_mul_f32 v[6:7], v[6:7], v[12:13]
	s_nop 0
	v_pk_mul_f32 v[6:7], v[14:15], v[6:7]
	s_nop 0
	v_cvt_pk_bf16_f32 v9, v6, v7
	s_waitcnt vmcnt(6)
	v_lshlrev_b32_e32 v6, 16, v192
	v_mul_f32_e32 v1, 0xbfb8aa3b, v6
	v_exp_f32_e32 v1, v1
	v_and_b32_e32 v7, 0xffff0000, v192
	global_store_dwordx2 v[10:11], v[8:9], off offset:160
	v_add_f32_e32 v1, 1.0, v1
	v_rcp_f32_e32 v8, v1
	v_pk_mul_f32 v[12:13], v[72:73], v[0:1] op_sel_hi:[1, 0]
	v_mul_f32_e32 v1, 0xbfb8aa3b, v7
	v_exp_f32_e32 v1, v1
	s_nop 0
	v_add_f32_e32 v1, 1.0, v1
	v_rcp_f32_e32 v9, v1
	s_nop 0
	v_pk_mul_f32 v[6:7], v[8:9], v[6:7]
	v_lshlrev_b32_e32 v8, 16, v193
	v_mul_f32_e32 v1, 0xbfb8aa3b, v8
	v_exp_f32_e32 v1, v1
	v_and_b32_e32 v9, 0xffff0000, v193
	v_pk_mul_f32 v[6:7], v[12:13], v[6:7]
	v_add_f32_e32 v1, 1.0, v1
	v_rcp_f32_e32 v4, v1
	v_pk_mul_f32 v[12:13], v[74:75], v[0:1] op_sel_hi:[1, 0]
	v_mul_f32_e32 v1, 0xbfb8aa3b, v9
	v_exp_f32_e32 v1, v1
	v_cvt_pk_bf16_f32 v6, v6, v7
	v_add_f32_e32 v1, 1.0, v1
	v_rcp_f32_e32 v5, v1
	s_nop 0
	v_pk_mul_f32 v[4:5], v[4:5], v[8:9]
	s_nop 0
	v_pk_mul_f32 v[4:5], v[12:13], v[4:5]
	s_nop 0
	v_cvt_pk_bf16_f32 v7, v4, v5
	s_waitcnt vmcnt(6)
	v_lshlrev_b32_e32 v4, 16, v194
	v_mul_f32_e32 v1, 0xbfb8aa3b, v4
	v_exp_f32_e32 v1, v1
	v_and_b32_e32 v5, 0xffff0000, v194
	global_store_dwordx2 v[10:11], v[6:7], off offset:192
	v_add_f32_e32 v1, 1.0, v1
	v_rcp_f32_e32 v6, v1
	v_pk_mul_f32 v[8:9], v[76:77], v[0:1] op_sel_hi:[1, 0]
	v_mul_f32_e32 v1, 0xbfb8aa3b, v5
	v_exp_f32_e32 v1, v1
	s_nop 0
	v_add_f32_e32 v1, 1.0, v1
	v_rcp_f32_e32 v7, v1
	s_nop 0
	v_pk_mul_f32 v[4:5], v[6:7], v[4:5]
	v_and_b32_e32 v7, 0xffff0000, v195
	v_lshlrev_b32_e32 v6, 16, v195
	v_mul_f32_e32 v1, 0xbfb8aa3b, v6
	v_mul_f32_e32 v3, 0xbfb8aa3b, v7
	v_exp_f32_e32 v1, v1
	v_exp_f32_e32 v3, v3
	v_pk_mul_f32 v[4:5], v[8:9], v[4:5]
	v_add_f32_e32 v1, 1.0, v1
	v_add_f32_e32 v3, 1.0, v3
	v_rcp_f32_e32 v2, v1
	v_rcp_f32_e32 v3, v3
	v_pk_mul_f32 v[0:1], v[78:79], v[0:1] op_sel_hi:[1, 0]
	v_pk_mul_f32 v[2:3], v[2:3], v[6:7]
	s_nop 0
	v_pk_mul_f32 v[0:1], v[0:1], v[2:3]
	v_cvt_pk_bf16_f32 v2, v4, v5
	v_cvt_pk_bf16_f32 v3, v0, v1
	global_store_dwordx2 v[10:11], v[2:3], off offset:224
	s_barrier
	s_load_dword s2, s[52:53], 0x0
	s_waitcnt lgkmcnt(0)
	s_add_i32 s26, s2, s26
	s_cmpk_gt_i32 s26, 0x1ff
	s_cbranch_scc1 .LBB0_671

; DEVI f32x4 mfma16(bf16x8 a, bf16x8 b, f32x4 c) { return __builtin_amdgcn_mfma_f32_16x16x32_bf16(a, b, c, 0, 0, 0); }
; template <bool OWN>
; DEVI void moba_half(const u16* Kt, const u16* Vs, const int kofs, const bf16x8 (&qb)[4], f32x4 (&oacc)[8], float& m, float& lsum,
;                     const bool lanesel, const int qinb, const int lane) {
;     ...
;   const int fr = lane & 15, fq = lane >> 4;
;   const float scl = 0.08838834764831845f * 1.4426950408889634f;
;   float s[8][4];
;   float mloc = -INFINITY;
;   const u16* kbase = Kt + (half * 128 + fr) * 136 + fq * 8;
; #pragma unroll
;   for (int kp = 0; kp < 4; ++kp) {
;     bf16x8 kf[2][4];
; #pragma unroll
;     for (int t = 0; t < 2; ++t)
; #pragma unroll
;       for (int ks = 0; ks < 4; ++ks) kf[t][ks] = *(const bf16x8*)(kbase + (2 * kp + t) * 16 * 136 + ks * 32);
;     f32x4 a0 = {0.f, 0.f, 0.f, 0.f}, a1 = {0.f, 0.f, 0.f, 0.f};
; #pragma unroll
;     for (int ks = 0; ks < 4; ++ks) { a0 = mfma16(kf[0][ks], qb[ks], a0); a1 = mfma16(kf[1][ks], qb[ks], a1); }
;     __builtin_amdgcn_sched_group_barrier(0x100, 8, 0);
;     __builtin_amdgcn_sched_group_barrier(0x008, 8, 0);
; #pragma unroll
;     for (int j = 0; j < 4; ++j) {
;       if (OWN) {
;         float v0 = ((kofs + (2 * kp) * 16 + fq * 4 + j) <= qinb) ? a0[j] * scl : -INFINITY;
;         float v1 = ((kofs + (2 * kp + 1) * 16 + fq * 4 + j) <= qinb) ? a1[j] * scl : -INFINITY;
;         s[2 * kp][j] = v0; s[2 * kp + 1][j] = v1;
;         mloc = fmaxf(mloc, fmaxf(v0, v1));
;       } else {
;         s[2 * kp][j] = a0[j]; s[2 * kp + 1][j] = a1[j];
;         mloc = fmaxf(mloc, fmaxf(a0[j], a1[j]));
;       }
;     }
;   }
; DEVI void moba_item(const Params& p, int l, int item) {
;     ...
;     const bool own = (cblk == qblk);
;     const bool lanesel = own ? true : (((mysel >> cblk) & 1u) != 0u);
;     if (own) {
;       if (chalf * 128 <= (qt & 1) * 128 + w * 16 + 15) moba_half<true>(Kc, Vc, chalf * 128, qb, oacc, m, lsum, true, qinb, lane);
;     } else if (__any(lanesel)) {
;       moba_half<false>(Kc, Vc, 0, qb, oacc, m, lsum, lanesel, qinb, lane);
.LBB0_661:
	s_and_b64 s[2:3], s[2:3], exec
	s_cselect_b32 s37, 0, s70
	s_cselect_b32 s36, s78, s72
	s_cmp_lg_u32 s38, s28
	s_mov_b64 s[2:3], -1
	s_cbranch_scc0 .LBB0_665
	v_lshrrev_b32_e32 v80, s38, v157
	v_and_b32_e32 v80, 1, v80
	v_cmp_eq_u32_e64 s[6:7], 1, v80
	v_bfe_u32 v80, v157, s38, 1
	v_cmp_ne_u32_e32 vcc, 0, v80
	s_cbranch_vccnz .Lmy_moba_body
	s_branch .LBB0_664
.Lmy_moba_body:
	v_add3_u32 v132, s37, v161, v162
	ds_read_b128 v[80:83], v132
	ds_read_b128 v[96:99], v132 offset:4352
	ds_read_b128 v[84:87], v132 offset:64
	ds_read_b128 v[100:103], v132 offset:4416
	ds_read_b128 v[88:91], v132 offset:128
	ds_read_b128 v[104:107], v132 offset:4480
	ds_read_b128 v[92:95], v132 offset:192
	ds_read_b128 v[108:111], v132 offset:4544
	v_cmp_lt_i32_e32 vcc, v232, v252
	s_waitcnt lgkmcnt(7)
	v_mfma_f32_16x16x32_bf16 v[80:83], v[80:83], v[32:35], 0
	s_waitcnt lgkmcnt(6)
	v_mfma_f32_16x16x32_bf16 v[96:99], v[96:99], v[32:35], 0
	s_waitcnt lgkmcnt(5)
	v_mfma_f32_16x16x32_bf16 v[80:83], v[84:87], v[36:39], v[80:83]
	s_waitcnt lgkmcnt(4)
	v_mfma_f32_16x16x32_bf16 v[84:87], v[100:103], v[36:39], v[96:99]
	s_waitcnt lgkmcnt(3)
	v_mfma_f32_16x16x32_bf16 v[80:83], v[88:91], v[40:43], v[80:83]
	s_waitcnt lgkmcnt(2)
	v_mfma_f32_16x16x32_bf16 v[84:87], v[104:107], v[40:43], v[84:87]
	s_waitcnt lgkmcnt(1)
	v_mfma_f32_16x16x32_bf16 v[100:103], v[92:95], v[44:47], v[80:83]
	s_waitcnt lgkmcnt(0)
	v_mfma_f32_16x16x32_bf16 v[96:99], v[108:111], v[44:47], v[84:87]
	ds_read_b128 v[104:107], v132 offset:13056
	s_nop 4
	v_max_f32_e32 v81, v100, v100
	v_max_f32_e32 v82, v101, v101
	v_max_f32_e32 v83, v103, v103
	ds_read_b128 v[84:87], v132 offset:8768
	v_max_f32_e32 v80, v96, v96
	v_max_f32_e32 v80, v81, v80
	v_max_f32_e32 v81, v97, v97
	v_max_f32_e32 v81, v82, v81
	v_max3_f32 v80, v80, s79, v81
	v_max_f32_e32 v81, v98, v98
	v_max_f32_e32 v82, v102, v102
	v_max_f32_e32 v81, v82, v81
	v_max_f32_e32 v82, v99, v99
	v_max_f32_e32 v82, v83, v82
	v_max3_f32 v120, v80, v81, v82
	ds_read_b128 v[80:83], v132 offset:8704
	ds_read_b128 v[108:111], v132 offset:13120
	ds_read_b128 v[88:91], v132 offset:8832
	ds_read_b128 v[112:115], v132 offset:13184
	ds_read_b128 v[92:95], v132 offset:8896
	ds_read_b128 v[116:119], v132 offset:13248
	s_waitcnt lgkmcnt(5)
	v_mfma_f32_16x16x32_bf16 v[80:83], v[80:83], v[32:35], 0
	v_mfma_f32_16x16x32_bf16 v[104:107], v[104:107], v[32:35], 0
	v_mfma_f32_16x16x32_bf16 v[80:83], v[84:87], v[36:39], v[80:83]
	s_waitcnt lgkmcnt(4)
	v_mfma_f32_16x16x32_bf16 v[84:87], v[108:111], v[36:39], v[104:107]
	s_waitcnt lgkmcnt(3)
	v_mfma_f32_16x16x32_bf16 v[80:83], v[88:91], v[40:43], v[80:83]
	s_waitcnt lgkmcnt(2)
	v_mfma_f32_16x16x32_bf16 v[84:87], v[112:115], v[40:43], v[84:87]
	s_waitcnt lgkmcnt(1)
	v_mfma_f32_16x16x32_bf16 v[108:111], v[92:95], v[44:47], v[80:83]
	s_waitcnt lgkmcnt(0)
	v_mfma_f32_16x16x32_bf16 v[104:107], v[116:119], v[44:47], v[84:87]
	ds_read_b128 v[112:115], v132 offset:21760
	s_nop 4
	v_max_f32_e32 v81, v108, v108
	v_max_f32_e32 v82, v109, v109
	v_max_f32_e32 v83, v111, v111
	ds_read_b128 v[84:87], v132 offset:17472
	v_max_f32_e32 v80, v104, v104
	v_max_f32_e32 v80, v81, v80
	v_max_f32_e32 v81, v105, v105
	v_max_f32_e32 v81, v82, v81
	v_max3_f32 v80, v120, v80, v81
	v_max_f32_e32 v81, v106, v106
	v_max_f32_e32 v82, v110, v110
	v_max_f32_e32 v81, v82, v81
	v_max_f32_e32 v82, v107, v107
	v_max_f32_e32 v82, v83, v82
	v_max3_f32 v128, v80, v81, v82
	ds_read_b128 v[80:83], v132 offset:17408
	ds_read_b128 v[116:119], v132 offset:21824
	ds_read_b128 v[88:91], v132 offset:17536
	ds_read_b128 v[120:123], v132 offset:21888
	ds_read_b128 v[92:95], v132 offset:17600
	ds_read_b128 v[124:127], v132 offset:21952
	s_waitcnt lgkmcnt(5)
	v_mfma_f32_16x16x32_bf16 v[80:83], v[80:83], v[32:35], 0
	v_mfma_f32_16x16x32_bf16 v[112:115], v[112:115], v[32:35], 0
	v_mfma_f32_16x16x32_bf16 v[80:83], v[84:87], v[36:39], v[80:83]
	s_waitcnt lgkmcnt(4)
	v_mfma_f32_16x16x32_bf16 v[84:87], v[116:119], v[36:39], v[112:115]
	s_waitcnt lgkmcnt(3)
	v_mfma_f32_16x16x32_bf16 v[80:83], v[88:91], v[40:43], v[80:83]
	s_waitcnt lgkmcnt(2)
	v_mfma_f32_16x16x32_bf16 v[84:87], v[120:123], v[40:43], v[84:87]
	s_waitcnt lgkmcnt(1)
	v_mfma_f32_16x16x32_bf16 v[112:115], v[92:95], v[44:47], v[80:83]
	s_waitcnt lgkmcnt(0)
	v_mfma_f32_16x16x32_bf16 v[124:127], v[124:127], v[44:47], v[84:87]
	ds_read_b128 v[116:119], v132 offset:30464
	s_nop 4
	v_max_f32_e32 v81, v112, v112
	v_max_f32_e32 v82, v113, v113
	v_max_f32_e32 v83, v115, v115
	ds_read_b128 v[84:87], v132 offset:26176
	v_max_f32_e32 v80, v124, v124
	v_max_f32_e32 v80, v81, v80
	v_max_f32_e32 v81, v125, v125
	v_max_f32_e32 v81, v82, v81
	v_max3_f32 v80, v128, v80, v81
	v_max_f32_e32 v81, v126, v126
	v_max_f32_e32 v82, v114, v114
	v_max_f32_e32 v81, v82, v81
	v_max_f32_e32 v82, v127, v127
	v_max_f32_e32 v82, v83, v82
	v_max3_f32 v136, v80, v81, v82
	ds_read_b128 v[80:83], v132 offset:26112
	ds_read_b128 v[120:123], v132 offset:30528
	ds_read_b128 v[88:91], v132 offset:26240
	ds_read_b128 v[128:131], v132 offset:30592
	ds_read_b128 v[92:95], v132 offset:26304
	ds_read_b128 v[132:135], v132 offset:30656
	s_waitcnt lgkmcnt(5)
	v_mfma_f32_16x16x32_bf16 v[80:83], v[80:83], v[32:35], 0
	v_mfma_f32_16x16x32_bf16 v[116:119], v[116:119], v[32:35], 0
	v_mfma_f32_16x16x32_bf16 v[80:83], v[84:87], v[36:39], v[80:83]
	s_waitcnt lgkmcnt(4)
	v_mfma_f32_16x16x32_bf16 v[84:87], v[120:123], v[36:39], v[116:119]
	s_waitcnt lgkmcnt(3)
	v_mfma_f32_16x16x32_bf16 v[80:83], v[88:91], v[40:43], v[80:83]
	s_waitcnt lgkmcnt(2)
	v_mfma_f32_16x16x32_bf16 v[84:87], v[128:131], v[40:43], v[84:87]
	s_waitcnt lgkmcnt(1)
; DEVI unsigned pk2bf(float a, float b) { hf2 v = {a, b}; hbf2 r = __builtin_convertvector(v, hbf2); return __builtin_bit_cast(unsigned, r); }
; DEVI float xq_max(float v) { v = fmaxf(v, __shfl_xor(v, 16)); v = fmaxf(v, __shfl_xor(v, 32)); return v; }
; template <bool OWN>
; DEVI void moba_half(const u16* Kt, const u16* Vs, const int kofs, const bf16x8 (&qb)[4], f32x4 (&oacc)[8], float& m, float& lsum,
;                     const bool lanesel, const int qinb, const int lane) {
;     ...
;   if (!OWN) mloc = lanesel ? mloc * scl : -INFINITY;
;   mloc = xq_max(mloc);
;   const float mnew = fmaxf(m, mloc);
;   const float alpha = __builtin_amdgcn_exp2f(m - mnew);
;   m = mnew;
;   lsum *= alpha;
; #pragma unroll
;   for (int ct = 0; ct < 8; ++ct) { oacc[ct][0] *= alpha; oacc[ct][1] *= alpha; oacc[ct][2] *= alpha; oacc[ct][3] *= alpha; }
;   const float msub = (OWN || lanesel) ? mnew : INFINITY;
;   bf16x8 pk[4];
; #pragma unroll
;   for (int pp = 0; pp < 4; ++pp) {
;     float e[8];
; #pragma unroll
;     for (int j = 0; j < 4; ++j) {
;       if (OWN) {
;         e[j] = __builtin_amdgcn_exp2f(s[2 * pp][j] - msub);
;         e[4 + j] = __builtin_amdgcn_exp2f(s[2 * pp + 1][j] - msub);
;       } else {
;         e[j] = __builtin_amdgcn_exp2f(__builtin_fmaf(s[2 * pp][j], scl, -msub));
;         e[4 + j] = __builtin_amdgcn_exp2f(__builtin_fmaf(s[2 * pp + 1][j], scl, -msub));
;       }
;     }
;     lsum += ((e[0] + e[1]) + (e[2] + e[3])) + ((e[4] + e[5]) + (e[6] + e[7]));
;     typedef __attribute__((ext_vector_type(4))) unsigned u32x4;
;     u32x4 pw = {pk2bf(e[0], e[1]), pk2bf(e[2], e[3]), pk2bf(e[4], e[5]), pk2bf(e[6], e[7])};
;     pk[pp] = __builtin_bit_cast(bf16x8, pw);
;   }
;   const int trr = (lane & 15) >> 2, trc = lane & 3;
;   const u16* vbase = Vs + (half * 128 + fq * 4 + trr) * 144 + trc * 4;
; #pragma unroll
;   for (int cp = 0; cp < 4; ++cp) {
;     bf16x4 vf[2][8];
; #pragma unroll
;     for (int t = 0; t < 2; ++t)
; #pragma unroll
;       for (int i = 0; i < 8; ++i) vf[t][i] = tr_read(vbase + i * 16 * 144 + (2 * cp + t) * 16);
	v_mfma_f32_16x16x32_bf16 v[144:147], v[92:95], v[44:47], v[80:83]
	s_waitcnt lgkmcnt(0)
	v_mfma_f32_16x16x32_bf16 v[148:151], v[132:135], v[44:47], v[84:87]
	s_nop 5
	v_max_f32_e32 v81, v144, v144
	s_nop 0
	v_max_f32_e32 v80, v148, v148
	v_max_f32_e32 v80, v81, v80
	v_max_f32_e32 v81, v149, v149
	v_max_f32_e32 v82, v145, v145
	v_max_f32_e32 v81, v82, v81
	v_max3_f32 v80, v136, v80, v81
	v_max_f32_e32 v81, v150, v150
	v_max_f32_e32 v82, v146, v146
	v_max_f32_e32 v81, v82, v81
	v_max_f32_e32 v82, v151, v151
	v_max_f32_e32 v83, v147, v147
	v_max_f32_e32 v82, v83, v82
	v_max3_f32 v80, v80, v81, v82
	v_mul_f32_e32 v80, 0x3e0293ee, v80
	v_cndmask_b32_e32 v81, v235, v232, vcc
	v_cndmask_b32_e64 v80, v233, v80, s[6:7]
	v_lshlrev_b32_e32 v81, 2, v81
	ds_bpermute_b32 v81, v81, v80
	v_cmp_lt_i32_e32 vcc, v226, v252
	s_waitcnt lgkmcnt(0)
	v_max_f32_e32 v81, v81, v81
	v_max_f32_e32 v80, v80, v81
	v_cndmask_b32_e32 v81, v235, v226, vcc
	v_lshlrev_b32_e32 v81, 2, v81
	ds_bpermute_b32 v81, v81, v80
	s_waitcnt lgkmcnt(0)
	v_max3_f32 v169, v167, v80, v81
	v_cndmask_b32_e64 v170, v233, -v169, s[6:7]
	v_fmamk_f32 v96, v96, 0x3e0293ee, v170
	v_fmamk_f32 v100, v100, 0x3e0293ee, v170
	v_exp_f32_e32 v117, v96
	v_fmamk_f32 v96, v101, 0x3e0293ee, v170
	v_fmamk_f32 v97, v97, 0x3e0293ee, v170
	v_fmamk_f32 v98, v98, 0x3e0293ee, v170
	v_exp_f32_e32 v116, v100
	v_exp_f32_e32 v96, v96
	v_exp_f32_e32 v97, v97
	v_fmamk_f32 v100, v102, 0x3e0293ee, v170
	v_exp_f32_e32 v101, v98
	v_fmamk_f32 v98, v103, 0x3e0293ee, v170
	v_fmamk_f32 v99, v99, 0x3e0293ee, v170
	v_exp_f32_e32 v100, v100
	v_exp_f32_e32 v98, v98
	v_exp_f32_e32 v99, v99
	v_pk_add_f32 v[102:103], v[116:117], v[96:97]
	v_cvt_pk_bf16_f32 v122, v117, v97
	v_fmamk_f32 v97, v104, 0x3e0293ee, v170
	v_pk_add_f32 v[118:119], v[100:101], v[98:99]
	v_cvt_pk_bf16_f32 v121, v100, v98
	v_exp_f32_e32 v98, v97
	v_fmamk_f32 v97, v109, 0x3e0293ee, v170
	v_pk_add_f32 v[102:103], v[102:103], v[118:119]
	v_exp_f32_e32 v100, v97
	v_fmamk_f32 v97, v105, 0x3e0293ee, v170
	v_pk_add_f32 v[102:103], v[102:103], v[102:103] op_sel_hi:[0,1]
	v_cvt_pk_bf16_f32 v120, v116, v96
	v_cvt_pk_bf16_f32 v123, v101, v99
	v_fmamk_f32 v96, v108, 0x3e0293ee, v170
	v_exp_f32_e32 v104, v97
	v_fmamk_f32 v97, v110, 0x3e0293ee, v170
	v_fmamk_f32 v101, v111, 0x3e0293ee, v170
	v_exp_f32_e32 v96, v96
	v_exp_f32_e32 v97, v97
	v_fmamk_f32 v99, v106, 0x3e0293ee, v170
	v_exp_f32_e32 v101, v101
	v_fmamk_f32 v102, v107, 0x3e0293ee, v170
	v_exp_f32_e32 v99, v99
	v_exp_f32_e32 v105, v102
	v_pk_add_f32 v[106:107], v[96:97], v[100:101]
	v_cvt_pk_bf16_f32 v117, v97, v101
	v_fmamk_f32 v97, v124, 0x3e0293ee, v170
	v_pk_add_f32 v[108:109], v[98:99], v[104:105]
	v_cvt_pk_bf16_f32 v118, v98, v104
	v_exp_f32_e32 v98, v97
	v_fmamk_f32 v97, v113, 0x3e0293ee, v170
	v_cvt_pk_bf16_f32 v116, v96, v100
	v_exp_f32_e32 v100, v97
	v_fmamk_f32 v97, v125, 0x3e0293ee, v170
	v_exp_f32_e32 v102, v97
	v_fmamk_f32 v97, v114, 0x3e0293ee, v170
	v_pk_add_f32 v[106:107], v[106:107], v[106:107] op_sel_hi:[0,1]
	v_exp_f32_e32 v104, v97
	v_fmamk_f32 v97, v126, 0x3e0293ee, v170
	v_pk_add_f32 v[108:109], v[108:109], v[108:109] op_sel_hi:[0,1]
	v_fmamk_f32 v96, v112, 0x3e0293ee, v170
	v_exp_f32_e32 v106, v97
	v_fmamk_f32 v97, v115, 0x3e0293ee, v170
	v_exp_f32_e32 v96, v96
	v_exp_f32_e32 v108, v97
	v_fmamk_f32 v97, v127, 0x3e0293ee, v170
	v_exp_f32_e32 v110, v97
	v_add_f32_e32 v97, v96, v100
	v_add_f32_e32 v101, v98, v102
	v_cvt_pk_bf16_f32 v124, v96, v100
	v_cvt_pk_bf16_f32 v126, v98, v102
	v_fmamk_f32 v98, v148, 0x3e0293ee, v170
	v_fmamk_f32 v100, v149, 0x3e0293ee, v170
	v_fmamk_f32 v102, v150, 0x3e0293ee, v170
	v_sub_f32_e32 v80, v167, v169
	v_cvt_pk_bf16_f32 v119, v99, v105
	v_add_f32_e32 v99, v104, v108
	v_add_f32_e32 v105, v106, v110
	v_cvt_pk_bf16_f32 v125, v104, v108
	v_cvt_pk_bf16_f32 v127, v106, v110
	v_fmamk_f32 v96, v144, 0x3e0293ee, v170
	v_exp_f32_e32 v106, v98
	v_fmamk_f32 v98, v145, 0x3e0293ee, v170
	v_exp_f32_e32 v108, v100
	v_fmamk_f32 v100, v146, 0x3e0293ee, v170
	v_exp_f32_e32 v152, v102
	v_fmamk_f32 v102, v147, 0x3e0293ee, v170
	v_exp_f32_e32 v82, v80
	v_exp_f32_e32 v96, v96
	v_exp_f32_e32 v98, v98
	v_exp_f32_e32 v100, v100
	v_exp_f32_e32 v104, v102
	v_fmac_f32_e32 v170, 0x3e0293ee, v151
	v_exp_f32_e32 v102, v170
	v_mul_f32_e32 v153, v166, v82
	v_pk_add_f32 v[110:111], v[96:97], v[98:99]
	v_pk_add_f32 v[112:113], v[100:101], v[104:105]
	v_pk_add_f32 v[114:115], v[152:153], v[102:103]
	v_pk_add_f32 v[110:111], v[110:111], v[112:113]
	v_pk_add_f32 v[112:113], v[106:107], v[108:109]
	v_pk_mul_f32 v[140:141], v[48:49], v[82:83] op_sel_hi:[1,0]
	v_pk_add_f32 v[112:113], v[112:113], v[114:115]
	v_cvt_pk_bf16_f32 v115, v152, v102
	v_pk_add_f32 v[110:111], v[110:111], v[112:113]
	v_cvt_pk_bf16_f32 v112, v96, v98
	v_lshlrev_b32_e32 v96, 1, v164
	v_add3_u32 v145, s36, v163, v96
	ds_read_b64_tr_b16 v[98:99], v145 offset:4608
	ds_read_b64_tr_b16 v[96:97], v145
	ds_read_b64_tr_b16 v[146:147], v145 offset:32
	ds_read_b64_tr_b16 v[148:149], v145 offset:4640
	v_cvt_pk_bf16_f32 v113, v100, v104
	ds_read_b64_tr_b16 v[100:101], v145 offset:9216
	ds_read_b64_tr_b16 v[102:103], v145 offset:13824
	ds_read_b64_tr_b16 v[150:151], v145 offset:9248
	ds_read_b64_tr_b16 v[152:153], v145 offset:13856
	v_pk_mul_f32 v[142:143], v[50:51], v[82:83] op_sel_hi:[1,0]
	v_pk_mul_f32 v[136:137], v[52:53], v[82:83] op_sel_hi:[1,0]
	v_pk_mul_f32 v[138:139], v[54:55], v[82:83] op_sel_hi:[1,0]
	v_cvt_pk_bf16_f32 v114, v106, v108
	ds_read_b64_tr_b16 v[104:105], v145 offset:18432
	ds_read_b64_tr_b16 v[106:107], v145 offset:23040
	ds_read_b64_tr_b16 v[170:171], v145 offset:18464
	ds_read_b64_tr_b16 v[172:173], v145 offset:23072
	v_add_f32_e32 v144, v110, v111
	ds_read_b64_tr_b16 v[108:109], v145 offset:27648
	ds_read_b64_tr_b16 v[110:111], v145 offset:32256
	ds_read_b64_tr_b16 v[174:175], v145 offset:27680
	ds_read_b64_tr_b16 v[176:177], v145 offset:32288
	s_waitcnt lgkmcnt(14)
; DEVI bf16x8 cat8(bf16x4 a, bf16x4 b) { return __builtin_shufflevector(a, b, 0, 1, 2, 3, 4, 5, 6, 7); }
; DEVI f32x4 mfma16(bf16x8 a, bf16x8 b, f32x4 c) { return __builtin_amdgcn_mfma_f32_16x16x32_bf16(a, b, c, 0, 0, 0); }
; template <bool OWN>
; DEVI void moba_half(const u16* Kt, const u16* Vs, const int kofs, const bf16x8 (&qb)[4], f32x4 (&oacc)[8], float& m, float& lsum,
;                     const bool lanesel, const int qinb, const int lane) {
;     ...
;   const int trr = (lane & 15) >> 2, trc = lane & 3;
;   const u16* vbase = Vs + (half * 128 + fq * 4 + trr) * 144 + trc * 4;
; #pragma unroll
;   for (int cp = 0; cp < 4; ++cp) {
;     bf16x4 vf[2][8];
; #pragma unroll
;     for (int t = 0; t < 2; ++t)
; #pragma unroll
;       for (int i = 0; i < 8; ++i) vf[t][i] = tr_read(vbase + i * 16 * 144 + (2 * cp + t) * 16);
; #pragma unroll
;     for (int pp = 0; pp < 4; ++pp) {
;       oacc[2 * cp] = mfma16(cat8(vf[0][2 * pp], vf[0][2 * pp + 1]), pk[pp], oacc[2 * cp]);
;       oacc[2 * cp + 1] = mfma16(cat8(vf[1][2 * pp], vf[1][2 * pp + 1]), pk[pp], oacc[2 * cp + 1]);
;     }
;     __builtin_amdgcn_sched_group_barrier(0x100, 16, 0);
;     __builtin_amdgcn_sched_group_barrier(0x008, 8, 0);
;   }
	v_mfma_f32_16x16x32_bf16 v[96:99], v[96:99], v[120:123], v[140:143]
	v_mul_f32_e64 v132, v56, v82
	v_mul_f32_e64 v133, v57, v82
	v_pk_mul_f32 v[134:135], v[58:59], v[82:83] op_sel_hi:[1,0]
	v_pk_mul_f32 v[128:129], v[60:61], v[82:83] op_sel_hi:[1,0]
	s_waitcnt lgkmcnt(12)
	v_mfma_f32_16x16x32_bf16 v[136:139], v[146:149], v[120:123], v[136:139]
	v_mul_f32_e64 v130, v62, v82
	v_mul_f32_e64 v131, v63, v82
	v_pk_mul_f32 v[92:93], v[64:65], v[82:83] op_sel_hi:[1,0]
	v_pk_mul_f32 v[94:95], v[66:67], v[82:83] op_sel_hi:[1,0]
	s_waitcnt lgkmcnt(10)
	v_mfma_f32_16x16x32_bf16 v[96:99], v[100:103], v[116:119], v[96:99]
	v_mul_f32_e64 v84, v68, v82
	v_mul_f32_e64 v85, v69, v82
	v_pk_mul_f32 v[86:87], v[70:71], v[82:83] op_sel_hi:[1,0]
	v_pk_mul_f32 v[88:89], v[72:73], v[82:83] op_sel_hi:[1,0]
	s_waitcnt lgkmcnt(8)
	v_mfma_f32_16x16x32_bf16 v[100:103], v[150:153], v[116:119], v[136:139]
	v_mul_f32_e64 v90, v74, v82
	v_mul_f32_e64 v91, v75, v82
	v_pk_mul_f32 v[80:81], v[76:77], v[82:83] op_sel_hi:[1,0]
	v_pk_mul_f32 v[82:83], v[78:79], v[82:83] op_sel_hi:[1,0]
	s_waitcnt lgkmcnt(6)
	v_mfma_f32_16x16x32_bf16 v[96:99], v[104:107], v[124:127], v[96:99]
	s_waitcnt lgkmcnt(4)
	v_mfma_f32_16x16x32_bf16 v[100:103], v[170:173], v[124:127], v[100:103]
	s_waitcnt lgkmcnt(2)
	v_mfma_f32_16x16x32_bf16 v[48:51], v[108:111], v[112:115], v[96:99]
	s_waitcnt lgkmcnt(0)
	v_mfma_f32_16x16x32_bf16 v[52:55], v[174:177], v[112:115], v[100:103]
	s_nop 1
	ds_read_b64_tr_b16 v[98:99], v145 offset:4672
	ds_read_b64_tr_b16 v[96:97], v145 offset:64
	ds_read_b64_tr_b16 v[146:147], v145 offset:96
	ds_read_b64_tr_b16 v[148:149], v145 offset:4704
	ds_read_b64_tr_b16 v[100:101], v145 offset:9280
	ds_read_b64_tr_b16 v[102:103], v145 offset:13888
	ds_read_b64_tr_b16 v[150:151], v145 offset:9312
	ds_read_b64_tr_b16 v[152:153], v145 offset:13920
	ds_read_b64_tr_b16 v[136:137], v145 offset:18496
	ds_read_b64_tr_b16 v[138:139], v145 offset:23104
	ds_read_b64_tr_b16 v[170:171], v145 offset:18528
	ds_read_b64_tr_b16 v[172:173], v145 offset:23136
	ds_read_b64_tr_b16 v[140:141], v145 offset:27712
	ds_read_b64_tr_b16 v[142:143], v145 offset:32320
	ds_read_b64_tr_b16 v[174:175], v145 offset:27744
	ds_read_b64_tr_b16 v[176:177], v145 offset:32352
	s_waitcnt lgkmcnt(14)
	v_mfma_f32_16x16x32_bf16 v[96:99], v[96:99], v[120:123], v[132:135]
	s_waitcnt lgkmcnt(12)
	v_mfma_f32_16x16x32_bf16 v[128:131], v[146:149], v[120:123], v[128:131]
	s_waitcnt lgkmcnt(10)
	v_mfma_f32_16x16x32_bf16 v[96:99], v[100:103], v[116:119], v[96:99]
	s_waitcnt lgkmcnt(8)
	v_mfma_f32_16x16x32_bf16 v[100:103], v[150:153], v[116:119], v[128:131]
	s_waitcnt lgkmcnt(6)
	v_mfma_f32_16x16x32_bf16 v[96:99], v[136:139], v[124:127], v[96:99]
	s_waitcnt lgkmcnt(4)
	v_mfma_f32_16x16x32_bf16 v[128:131], v[170:173], v[124:127], v[100:103]
	s_waitcnt lgkmcnt(2)
	v_mfma_f32_16x16x32_bf16 v[56:59], v[140:143], v[112:115], v[96:99]
	s_waitcnt lgkmcnt(0)
	v_mfma_f32_16x16x32_bf16 v[60:63], v[174:177], v[112:115], v[128:131]
	ds_read_b64_tr_b16 v[146:147], v145 offset:160
	ds_read_b64_tr_b16 v[148:149], v145 offset:4768
	ds_read_b64_tr_b16 v[132:133], v145 offset:9344
	s_nop 0
	ds_read_b64_tr_b16 v[130:131], v145 offset:4736
	ds_read_b64_tr_b16 v[128:129], v145 offset:128
	ds_read_b64_tr_b16 v[134:135], v145 offset:13952
	ds_read_b64_tr_b16 v[150:151], v145 offset:9376
	ds_read_b64_tr_b16 v[152:153], v145 offset:13984
	ds_read_b64_tr_b16 v[136:137], v145 offset:18560
	ds_read_b64_tr_b16 v[138:139], v145 offset:23168
	ds_read_b64_tr_b16 v[170:171], v145 offset:18592
	ds_read_b64_tr_b16 v[172:173], v145 offset:23200
	ds_read_b64_tr_b16 v[140:141], v145 offset:27776
	ds_read_b64_tr_b16 v[142:143], v145 offset:32384
	ds_read_b64_tr_b16 v[174:175], v145 offset:27808
	ds_read_b64_tr_b16 v[176:177], v145 offset:32416
	s_waitcnt lgkmcnt(11)
	v_mfma_f32_16x16x32_bf16 v[92:95], v[128:131], v[120:123], v[92:95]
	v_mfma_f32_16x16x32_bf16 v[84:87], v[146:149], v[120:123], v[84:87]
	s_waitcnt lgkmcnt(10)
	v_mfma_f32_16x16x32_bf16 v[92:95], v[132:135], v[116:119], v[92:95]
	s_waitcnt lgkmcnt(8)
	v_mfma_f32_16x16x32_bf16 v[84:87], v[150:153], v[116:119], v[84:87]
	s_waitcnt lgkmcnt(6)
	v_mfma_f32_16x16x32_bf16 v[92:95], v[136:139], v[124:127], v[92:95]
	s_waitcnt lgkmcnt(4)
	v_mfma_f32_16x16x32_bf16 v[84:87], v[170:173], v[124:127], v[84:87]
	s_waitcnt lgkmcnt(2)
	v_mfma_f32_16x16x32_bf16 v[64:67], v[140:143], v[112:115], v[92:95]
	s_waitcnt lgkmcnt(0)
	v_mfma_f32_16x16x32_bf16 v[68:71], v[174:177], v[112:115], v[84:87]
	ds_read_b64_tr_b16 v[130:131], v145 offset:4800
	ds_read_b64_tr_b16 v[128:129], v145 offset:192
	ds_read_b64_tr_b16 v[146:147], v145 offset:224
	ds_read_b64_tr_b16 v[148:149], v145 offset:4832
	ds_read_b64_tr_b16 v[132:133], v145 offset:9408
	ds_read_b64_tr_b16 v[134:135], v145 offset:14016
	ds_read_b64_tr_b16 v[150:151], v145 offset:9440
	ds_read_b64_tr_b16 v[152:153], v145 offset:14048
	ds_read_b64_tr_b16 v[136:137], v145 offset:18624
	ds_read_b64_tr_b16 v[138:139], v145 offset:23232
	ds_read_b64_tr_b16 v[170:171], v145 offset:18656
	ds_read_b64_tr_b16 v[172:173], v145 offset:23264
	ds_read_b64_tr_b16 v[140:141], v145 offset:27840
	ds_read_b64_tr_b16 v[142:143], v145 offset:32448
	ds_read_b64_tr_b16 v[174:175], v145 offset:27872
	ds_read_b64_tr_b16 v[176:177], v145 offset:32480
	s_waitcnt lgkmcnt(14)
	v_mfma_f32_16x16x32_bf16 v[88:91], v[128:131], v[120:123], v[88:91]
	s_waitcnt lgkmcnt(12)
	v_mfma_f32_16x16x32_bf16 v[80:83], v[146:149], v[120:123], v[80:83]
	s_waitcnt lgkmcnt(10)
	v_mfma_f32_16x16x32_bf16 v[88:91], v[132:135], v[116:119], v[88:91]
	s_waitcnt lgkmcnt(8)
	v_mfma_f32_16x16x32_bf16 v[80:83], v[150:153], v[116:119], v[80:83]
	s_waitcnt lgkmcnt(6)
	v_mfma_f32_16x16x32_bf16 v[88:91], v[136:139], v[124:127], v[88:91]
	s_waitcnt lgkmcnt(4)
	v_mfma_f32_16x16x32_bf16 v[80:83], v[170:173], v[124:127], v[80:83]
	s_waitcnt lgkmcnt(2)
	v_mfma_f32_16x16x32_bf16 v[72:75], v[140:143], v[112:115], v[88:91]
	s_waitcnt lgkmcnt(0)
	v_mfma_f32_16x16x32_bf16 v[76:79], v[174:177], v[112:115], v[80:83]
	v_mov_b32_e32 v166, v144
	v_mov_b32_e32 v167, v169

; DEVI void moba_item(const Params& p, int l, int item) {
;     ...
;     const bool own = (cblk == qblk);
;     const bool lanesel = own ? true : (((mysel >> cblk) & 1u) != 0u);
;     if (own) {
;       if (chalf * 128 <= (qt & 1) * 128 + w * 16 + 15) moba_half<true>(Kc, Vc, chalf * 128, qb, oacc, m, lsum, true, qinb, lane);
;     } else if (__any(lanesel)) {
;       moba_half<false>(Kc, Vc, 0, qb, oacc, m, lsum, lanesel, qinb, lane);
;     }
;     __syncthreads();
;     cblk = nblk; chalf = nhalf; nblk = n2blk; nhalf = n2half; par ^= 1;
.LBB0_668:
	s_or_b64 exec, exec, s[2:3]
.Lmy_moba_endstage:
	v_readfirstlane_b32 s6, v234
	s_cmpk_lt_u32 s6, 0x100
	s_cbranch_scc0 .LBB0_669
	s_cmp_eq_u32 s31, 0
	s_cselect_b64 s[2:3], -1, 0
	s_and_b64 vcc, exec, s[20:21]
	s_cbranch_vccz .Lmy_moba_658
	s_mov_b64 s[22:23], 0
	s_mov_b32 s34, -1
	s_branch .LBB0_669

; DEVI void moba_item(const Params& p, int l, int item) {
;     ...
;   while (cblk >= 0) {
;     u16* Kc = par ? Kb1 : Kb0; u16* Vc = par ? Vb1 : Vb0;
;     u16* Kn = par ? Kb0 : Kb1; u16* Vn = par ? Vb0 : Vb1;
;     int n2blk = -1, n2half = 0;
;     if (nblk >= 0) {
; #pragma unroll
;       for (int i = 0; i < 4; ++i) {
;         *(bf16x8*)(Kn + (kkey + 32 * i) * 136 + kdg * 8) = pk_[i];
;         *(bf16x8*)(Vn + (kkey + 32 * i) * 144 + kdg * 8) = pv_[i];
;       }
;       MOBA_NEXT(nblk, nhalf, n2blk, n2half);
;       if (n2blk >= 0) MOBA_LOAD(n2blk, n2half);
;     }
;     const bool own = (cblk == qblk);
;     const bool lanesel = own ? true : (((mysel >> cblk) & 1u) != 0u);
;     if (own) {
;       if (chalf * 128 <= (qt & 1) * 128 + w * 16 + 15) moba_half<true>(Kc, Vc, chalf * 128, qb, oacc, m, lsum, true, qinb, lane);
;     } else if (__any(lanesel)) {
;       moba_half<false>(Kc, Vc, 0, qb, oacc, m, lsum, lanesel, qinb, lane);
;     }
;     __syncthreads();
;     cblk = nblk; chalf = nhalf; nblk = n2blk; nhalf = n2half; par ^= 1;
;   }
.LBB0_669:
	v_cndmask_b32_e64 v168, 0, 1, s[10:11]
	s_andn2_b64 vcc, exec, s[20:21]
	s_xor_b32 s31, s31, 1
	s_waitcnt lgkmcnt(0)
	s_barrier
	s_cbranch_vccz .LBB0_493
	s_mov_b64 s[10:11], s[22:23]
	s_mov_b32 s38, s35
	s_branch .LBB0_656
